# baseline (speedup 1.0000x reference)
.LBB0_224:
	v_ashrrev_i32_e32 v138, 5, v158
	v_add_u32_e32 v139, s91, v138
	v_mov_b64_e32 v[150:151], s[92:93]
	v_mad_u64_u32 v[142:143], s[0:1], v139, s47, v[150:151]
	v_ashrrev_i32_e32 v141, 31, v139
	v_mov_b32_e32 v144, v143
	v_mad_u64_u32 v[144:145], s[0:1], v141, s47, v[144:145]
	v_lshlrev_b32_e32 v128, 4, v158
	v_mov_b32_e32 v143, v144
	v_and_b32_e32 v128, 0x1f0, v128
	v_mul_lo_u32 v137, v138, s49
	v_lshl_add_u64 v[142:143], v[142:143], 1, s[96:97]
	v_add_u32_e32 v139, 16, v138
	v_cvt_pk_bf16_f32 v130, v130, v131
	v_cvt_pk_bf16_f32 v131, v132, v133
	v_add_u32_e32 v140, v128, v137
	v_lshl_add_u64 v[142:143], v[142:143], 0, v[128:129]
	v_add_u32_e32 v141, s91, v139
	ds_write_b64 v136, v[130:131] offset:25632
	s_waitcnt lgkmcnt(0)
	s_barrier
	v_add_u32_e32 v202, 0x2100, v140
	ds_read_b128 v[170:173], v140
	ds_read_b128 v[174:177], v202
	ds_read_b128 v[178:181], v202 offset:8448
	ds_read_b128 v[182:185], v202 offset:16896
	ds_read_b128 v[186:189], v202 offset:25344
	ds_read_b128 v[190:193], v202 offset:33792
	ds_read_b128 v[194:197], v202 offset:42240
	ds_read_b128 v[198:201], v202 offset:50688
	s_waitcnt lgkmcnt(7)
	global_store_dwordx4 v[142:143], v[170:173], off sc1
	s_nop 1
	v_mad_u64_u32 v[142:143], s[0:1], v141, s47, v[150:151]
	v_ashrrev_i32_e32 v145, 31, v141
	v_mov_b32_e32 v144, v143
	v_mad_u64_u32 v[144:145], s[0:1], v145, s47, v[144:145]
	v_mov_b32_e32 v143, v144
	v_add_u32_e32 v130, 0x2100, v137
	v_lshl_add_u64 v[142:143], v[142:143], 1, s[96:97]
	v_add_u32_e32 v137, v128, v130
	v_lshl_add_u64 v[142:143], v[142:143], 0, v[128:129]
	v_add_u32_e32 v141, 32, v138
	s_waitcnt lgkmcnt(6)
	global_store_dwordx4 v[142:143], v[174:177], off sc1
	s_nop 1
	v_add_u32_e32 v142, s91, v141
	v_ashrrev_i32_e32 v145, 31, v142
	v_mad_u64_u32 v[142:143], s[0:1], v142, s47, v[150:151]
	v_mov_b32_e32 v144, v143
	v_mad_u64_u32 v[144:145], s[0:1], v145, s47, v[144:145]
	v_mov_b32_e32 v143, v144
	v_lshl_add_u64 v[142:143], v[142:143], 1, s[96:97]
	v_lshl_add_u64 v[142:143], v[142:143], 0, v[128:129]
	s_waitcnt lgkmcnt(5)
	global_store_dwordx4 v[142:143], v[178:181], off sc1
	s_nop 1
	v_add_u32_e32 v142, 48, v138
	v_add_u32_e32 v143, s91, v142
	v_mad_u64_u32 v[144:145], s[0:1], v143, s47, v[150:151]
	v_ashrrev_i32_e32 v161, 31, v143
	v_mov_b32_e32 v146, v145
	v_mad_u64_u32 v[162:163], s[0:1], v161, s47, v[146:147]
	v_mov_b32_e32 v145, v162
	v_lshl_add_u64 v[144:145], v[144:145], 1, s[96:97]
	v_lshl_add_u64 v[144:145], v[144:145], 0, v[128:129]
	v_add_u32_e32 v143, 64, v138
	s_waitcnt lgkmcnt(4)
	global_store_dwordx4 v[144:145], v[182:185], off sc1
	s_nop 1
	v_add_u32_e32 v144, s91, v143
	v_ashrrev_i32_e32 v161, 31, v144
	v_mad_u64_u32 v[144:145], s[0:1], v144, s47, v[150:151]
	v_mov_b32_e32 v146, v145
	v_mad_u64_u32 v[162:163], s[0:1], v161, s47, v[146:147]
	v_mov_b32_e32 v145, v162
	v_lshl_add_u64 v[144:145], v[144:145], 1, s[96:97]
	v_lshl_add_u64 v[144:145], v[144:145], 0, v[128:129]
	s_waitcnt lgkmcnt(3)
	global_store_dwordx4 v[144:145], v[186:189], off sc1
	s_nop 1
	v_add_u32_e32 v144, 0x50, v138
	v_add_u32_e32 v145, s91, v144
	v_mad_u64_u32 v[162:163], s[0:1], v145, s47, v[150:151]
	v_ashrrev_i32_e32 v161, 31, v145
	v_mov_b32_e32 v146, v163
	v_mad_u64_u32 v[164:165], s[0:1], v161, s47, v[146:147]
	v_mov_b32_e32 v163, v164
	v_lshl_add_u64 v[162:163], v[162:163], 1, s[96:97]
	v_add_u32_e32 v145, 0x60, v138
	v_lshl_add_u64 v[162:163], v[162:163], 0, v[128:129]
	v_add_u32_e32 v146, s91, v145
	s_waitcnt lgkmcnt(2)
	global_store_dwordx4 v[162:163], v[190:193], off sc1
	s_nop 1
	v_mad_u64_u32 v[162:163], s[0:1], v146, s47, v[150:151]
	v_ashrrev_i32_e32 v161, 31, v146
	v_mov_b32_e32 v146, v163
	v_mad_u64_u32 v[164:165], s[0:1], v161, s47, v[146:147]
	v_mov_b32_e32 v163, v164
	v_add_u32_e32 v146, 0x70, v138
	v_lshl_add_u64 v[162:163], v[162:163], 1, s[96:97]
	v_add_u32_e32 v161, s91, v146
	v_lshl_add_u64 v[162:163], v[162:163], 0, v[128:129]
	v_mad_u64_u32 v[150:151], s[0:1], v161, s47, v[150:151]
	s_waitcnt lgkmcnt(1)
	global_store_dwordx4 v[162:163], v[194:197], off sc1
	s_nop 1
	v_ashrrev_i32_e32 v163, 31, v161
	v_mov_b32_e32 v162, v151
	v_mad_u64_u32 v[162:163], s[0:1], v163, s47, v[162:163]
	v_mov_b32_e32 v151, v162
	v_lshl_add_u64 v[150:151], v[150:151], 1, s[96:97]
	v_lshl_add_u64 v[150:151], v[150:151], 0, v[128:129]
	s_waitcnt lgkmcnt(0)
	global_store_dwordx4 v[150:151], v[198:201], off sc1
	s_nop 1
	s_and_b64 vcc, exec, s[4:5]
	v_mov_b32_e32 v130, v60
	v_mov_b32_e32 v131, v61
	v_mov_b32_e32 v132, v62
	v_mov_b32_e32 v133, v63
	s_barrier
	s_cbranch_vccnz .LBB0_226
	v_max_f32_e32 v130, v60, v60
	v_max_f32_e32 v131, v61, v61
	v_max_f32_e32 v132, v62, v62
	v_max_f32_e32 v133, v63, v63
	v_max_f32_e32 v130, 0, v130
	v_max_f32_e32 v131, 0, v131
	v_max_f32_e32 v132, 0, v132
	v_max_f32_e32 v133, 0, v133
	v_pk_mul_f32 v[130:131], v[130:131], v[130:131]
	v_pk_mul_f32 v[132:133], v[132:133], v[132:133]

.LBB0_256:
	v_cvt_pk_bf16_f32 v132, v132, v133
	s_nop 0
	v_cvt_pk_bf16_f32 v133, v130, v131
	ds_write_b64 v136, v[132:133] offset:25632
	v_add_u32_e32 v136, s87, v138
	v_mov_b64_e32 v[150:151], s[92:93]
	v_mad_u64_u32 v[162:163], s[0:1], v136, s47, v[150:151]
	v_ashrrev_i32_e32 v138, 31, v136
	v_mov_b32_e32 v136, v163
	v_mad_u64_u32 v[164:165], s[0:1], v138, s47, v[136:137]
	v_mov_b32_e32 v163, v164
	v_add_u32_e32 v136, s87, v139
	v_lshl_add_u64 v[162:163], v[162:163], 1, s[96:97]
	v_mad_u64_u32 v[138:139], s[0:1], v136, s47, v[150:151]
	s_waitcnt lgkmcnt(0)
	s_barrier
	v_add_u32_e32 v202, 0x2100, v140
	ds_read_b128 v[170:173], v140
	ds_read_b128 v[174:177], v202
	ds_read_b128 v[178:181], v202 offset:8448
	ds_read_b128 v[182:185], v202 offset:16896
	ds_read_b128 v[186:189], v202 offset:25344
	ds_read_b128 v[190:193], v202 offset:33792
	ds_read_b128 v[194:197], v202 offset:42240
	ds_read_b128 v[198:201], v202 offset:50688
	v_lshl_add_u64 v[162:163], v[162:163], 0, v[128:129]
	v_ashrrev_i32_e32 v140, 31, v136
	v_mov_b32_e32 v136, v139
	s_waitcnt lgkmcnt(7)
	global_store_dwordx4 v[162:163], v[170:173], off sc1
	s_nop 1
	v_mad_u64_u32 v[162:163], s[0:1], v140, s47, v[136:137]
	v_mov_b32_e32 v139, v162
	v_lshl_add_u64 v[138:139], v[138:139], 1, s[96:97]
	v_lshl_add_u64 v[138:139], v[138:139], 0, v[128:129]
	v_add_u32_e32 v136, s87, v141
	s_waitcnt lgkmcnt(6)
	global_store_dwordx4 v[138:139], v[174:177], off sc1
	s_nop 1
	v_mad_u64_u32 v[138:139], s[0:1], v136, s47, v[150:151]
	v_ashrrev_i32_e32 v140, 31, v136
	v_mov_b32_e32 v136, v139
	v_mad_u64_u32 v[140:141], s[0:1], v140, s47, v[136:137]
	v_mov_b32_e32 v139, v140
	v_lshl_add_u64 v[138:139], v[138:139], 1, s[96:97]
	v_lshl_add_u64 v[138:139], v[138:139], 0, v[128:129]
	v_add_u32_e32 v136, s87, v142
	s_waitcnt lgkmcnt(5)
	global_store_dwordx4 v[138:139], v[178:181], off sc1
	s_nop 1
	v_mad_u64_u32 v[138:139], s[0:1], v136, s47, v[150:151]
	v_ashrrev_i32_e32 v140, 31, v136
	v_mov_b32_e32 v136, v139
	v_mad_u64_u32 v[140:141], s[0:1], v140, s47, v[136:137]
	v_mov_b32_e32 v139, v140
	v_lshl_add_u64 v[138:139], v[138:139], 1, s[96:97]
	v_lshl_add_u64 v[138:139], v[138:139], 0, v[128:129]
	v_add_u32_e32 v136, s87, v143
	s_waitcnt lgkmcnt(4)
	global_store_dwordx4 v[138:139], v[182:185], off sc1
	s_nop 1
	v_mad_u64_u32 v[138:139], s[0:1], v136, s47, v[150:151]
	v_ashrrev_i32_e32 v140, 31, v136
	v_mov_b32_e32 v136, v139
	v_mad_u64_u32 v[140:141], s[0:1], v140, s47, v[136:137]
	v_mov_b32_e32 v139, v140
	v_lshl_add_u64 v[138:139], v[138:139], 1, s[96:97]
	v_lshl_add_u64 v[138:139], v[138:139], 0, v[128:129]
	v_add_u32_e32 v136, s87, v144
	s_waitcnt lgkmcnt(3)
	global_store_dwordx4 v[138:139], v[186:189], off sc1
	s_nop 1
	v_mad_u64_u32 v[138:139], s[0:1], v136, s47, v[150:151]
	v_ashrrev_i32_e32 v140, 31, v136
	v_mov_b32_e32 v136, v139
	v_mad_u64_u32 v[140:141], s[0:1], v140, s47, v[136:137]
	v_mov_b32_e32 v139, v140
	v_lshl_add_u64 v[138:139], v[138:139], 1, s[96:97]
	v_lshl_add_u64 v[138:139], v[138:139], 0, v[128:129]
	v_add_u32_e32 v136, s87, v145
	s_waitcnt lgkmcnt(2)
	global_store_dwordx4 v[138:139], v[190:193], off sc1
	s_nop 1
	v_mad_u64_u32 v[138:139], s[0:1], v136, s47, v[150:151]
	v_ashrrev_i32_e32 v140, 31, v136
	v_mov_b32_e32 v136, v139
	v_mad_u64_u32 v[140:141], s[0:1], v140, s47, v[136:137]
	v_mov_b32_e32 v139, v140
	v_lshl_add_u64 v[138:139], v[138:139], 1, s[96:97]
	v_lshl_add_u64 v[138:139], v[138:139], 0, v[128:129]
	s_waitcnt lgkmcnt(1)
	global_store_dwordx4 v[138:139], v[194:197], off sc1
	s_nop 1
	v_add_u32_e32 v136, s87, v146
	v_ashrrev_i32_e32 v139, 31, v136
	v_mad_u64_u32 v[136:137], s[0:1], v136, s47, v[150:151]
	v_mov_b32_e32 v138, v137
	v_mad_u64_u32 v[138:139], s[0:1], v139, s47, v[138:139]
	v_mov_b32_e32 v137, v138
	v_lshl_add_u64 v[136:137], v[136:137], 1, s[96:97]
	v_lshl_add_u64 v[136:137], v[136:137], 0, v[128:129]
	s_waitcnt lgkmcnt(0)
	global_store_dwordx4 v[136:137], v[198:201], off sc1
	s_nop 1
	s_mov_b64 s[2:3], 0
	s_barrier
